# P0b modulate_rows: 12 loads of a row issued up front
# baseline (speedup 1.0000x reference)
.LBB0_96:
	s_min_i32 s5, s16, 0x4000
	s_ashr_i32 s5, s5, 11
	s_mul_hi_i32 s12, s5, 0x9000
	s_mul_i32 s5, s5, 0x9000
	s_add_u32 s24, s2, s5
	s_addc_u32 s25, s3, s12
	v_lshl_add_u64 v[20:21], s[24:25], 0, v[4:5]
	v_add_co_u32_e32 v22, vcc, s22, v20
	v_lshl_add_u64 v[18:19], s[20:21], 0, v[4:5]
	s_nop 0
	v_addc_co_u32_e32 v23, vcc, 0, v21, vcc
	v_lshl_add_u64 v[26:27], v[20:21], 0, s[14:15]
	global_load_dwordx4 v[30:33], v[18:19], off
	global_load_dwordx4 v[34:37], v[22:23], off
	global_load_dwordx4 v[38:41], v[20:21], off
	global_load_dwordx4 v[42:45], v[26:27], off offset:1024
	global_load_dwordx4 v[46:49], v[18:19], off offset:1024
	global_load_dwordx4 v[50:53], v[20:21], off offset:1024
	global_load_dwordx4 v[54:57], v[26:27], off offset:2048
	global_load_dwordx4 v[58:61], v[18:19], off offset:2048
	global_load_dwordx4 v[62:65], v[20:21], off offset:2048
	global_load_dwordx4 v[66:69], v[26:27], off offset:3072
	global_load_dwordx4 v[70:73], v[18:19], off offset:3072
	global_load_dwordx4 v[74:77], v[20:21], off offset:3072
	s_waitcnt vmcnt(0)
	s_lshl_b64 s[18:19], s[18:19], 11
	v_lshl_add_u64 v[22:23], v[0:1], 0, s[18:19]
	v_lshl_add_u64 v[24:25], v[2:3], 0, s[18:19]
	s_add_u32 s16, s16, s38
	s_addc_u32 s17, s17, s39
	s_add_u32 s8, s8, s10
	s_addc_u32 s9, s9, s11
	s_cmpk_lt_i32 s16, 0x4800
	v_cvt_pk_f16_f32 v29, v32, v33
	v_pk_add_f32 v[10:11], v[34:35], 1.0 op_sel_hi:[1, 0]
	v_cvt_pk_f16_f32 v28, v30, v31
	v_pk_add_f32 v[12:13], v[36:37], 1.0 op_sel_hi:[1, 0]
	v_pk_fma_f32 v[6:7], v[30:31], v[10:11], v[38:39]
	global_store_dwordx2 v[22:23], v[28:29], off
	v_pk_fma_f32 v[8:9], v[32:33], v[12:13], v[40:41]
	v_cvt_pk_bf16_f32 v6, v6, v7
	s_nop 0
	v_cvt_pk_bf16_f32 v7, v8, v9
	global_store_dwordx2 v[24:25], v[6:7], off
	s_nop 0
	v_pk_add_f32 v[6:7], v[42:43], 1.0 op_sel_hi:[1, 0]
	v_pk_add_f32 v[8:9], v[44:45], 1.0 op_sel_hi:[1, 0]
	v_cvt_pk_f16_f32 v29, v48, v49
	v_cvt_pk_f16_f32 v28, v46, v47
	v_pk_fma_f32 v[6:7], v[46:47], v[6:7], v[50:51]
	v_pk_fma_f32 v[8:9], v[48:49], v[8:9], v[52:53]
	global_store_dwordx2 v[22:23], v[28:29], off offset:512
	v_cvt_pk_bf16_f32 v6, v6, v7
	v_cvt_pk_bf16_f32 v7, v8, v9
	global_store_dwordx2 v[24:25], v[6:7], off offset:512
	s_nop 0
	v_pk_add_f32 v[6:7], v[54:55], 1.0 op_sel_hi:[1, 0]
	v_pk_add_f32 v[8:9], v[56:57], 1.0 op_sel_hi:[1, 0]
	v_cvt_pk_f16_f32 v29, v60, v61
	v_cvt_pk_f16_f32 v28, v58, v59
	v_pk_fma_f32 v[6:7], v[58:59], v[6:7], v[62:63]
	v_pk_fma_f32 v[8:9], v[60:61], v[8:9], v[64:65]
	global_store_dwordx2 v[22:23], v[28:29], off offset:1024
	v_cvt_pk_bf16_f32 v6, v6, v7
	v_cvt_pk_bf16_f32 v7, v8, v9
	global_store_dwordx2 v[24:25], v[6:7], off offset:1024
	s_nop 0
	v_pk_add_f32 v[6:7], v[66:67], 1.0 op_sel_hi:[1, 0]
	v_pk_add_f32 v[8:9], v[68:69], 1.0 op_sel_hi:[1, 0]
	v_cvt_pk_f16_f32 v19, v72, v73
	v_cvt_pk_f16_f32 v18, v70, v71
	v_pk_fma_f32 v[6:7], v[70:71], v[6:7], v[74:75]
	v_pk_fma_f32 v[8:9], v[72:73], v[8:9], v[76:77]
	global_store_dwordx2 v[22:23], v[18:19], off offset:1536
	v_cvt_pk_bf16_f32 v6, v6, v7
	v_cvt_pk_bf16_f32 v7, v8, v9
	global_store_dwordx2 v[24:25], v[6:7], off offset:1536
	v_mov_b32_e32 v10, v70
	v_mov_b32_e32 v11, v71
	v_mov_b32_e32 v12, v72
	v_mov_b32_e32 v13, v73
	v_mov_b32_e32 v14, v74
	v_mov_b32_e32 v15, v75
	v_mov_b32_e32 v16, v76
	v_mov_b32_e32 v17, v77
	s_cbranch_scc0 .LBB0_99
